# v076 + RG-LRU scan writes packed row-pair dwords (32 ds_write_b32, no extra VALU) into the dead XC region; Y-store stage splits halves with v_perm into two row stores
# speedup vs baseline: 1.0125x; 1.0125x over previous
; #define LAS __attribute__((address_space(3)))
; DI unsigned pk2(float a, float b) { f32x2 v = {a, b}; bf2_t r = __builtin_convertvector(v, bf2_t); return __builtin_bit_cast(unsigned, r); }
; DI void phase_rglru(const Params& p, unsigned char* shm) {
;     ...
;             if (tid < 192) {
; #pragma unroll 8
;                 for (int r = 0; r < 64; ++r) {
;                     const float om = __uint_as_float((unsigned)*(const LAS bf16_t*)(lds + LAo + r * TR + tid * 2) << 16);
;                     const float bt = __uint_as_float((unsigned)*(const LAS bf16_t*)(lds + BTo + r * TR + tid * 2) << 16);
;                     const float g = __uint_as_float((unsigned)*(const LAS bf16_t*)(lds + GT + r * TR + tid * 2) << 16);
;                     hst = (hst - om * hst) + bt;
;                     *(LAS bf16_t*)(lds + GT + r * TR + tid * 2) = (bf16_t)(pk2(hst * g, 0.f) & 0xffffu);
;                 }
;             } else if (tid >= 256 && tid < 328) {
;                 const int i = tid - 256, r = i / 24, cc = i % 24;
;                 const u32x4 v = *(const LAS u32x4*)(lds + XR + (64 + r) * TR + cc * 16);
;                 *(LAS u32x4*)(lds + XR + r * TR + cc * 16) = v;
;             }
;             __syncthreads();
;             const size_t ob = base + (size_t)tile * 64 * 1536;
; #pragma unroll
;             for (int j = 0; j < 3; ++j) *(u32x4*)(Y + ob + goff[j]) = *(const LAS u32x4*)(lds + GT + loff[j]);
.LBB0_842:
	s_or_b64 exec, exec, s[2:3]
	s_waitcnt lgkmcnt(0)
	s_barrier
	s_lshl_b64 s[2:3], s[10:11], 1
	s_add_u32 s2, s62, s2
	s_addc_u32 s3, s63, s3
	v_mov_b32_e32 v132, 0x5040100
	v_mov_b32_e32 v133, 0x7060302
	v_mul_hi_i32 v120, v192, s71
	v_ashrrev_i32_e32 v120, 2, v120
	v_mul_u32_u24_e32 v121, 24, v120
	v_sub_u32_e32 v121, v192, v121
	v_mul_u32_u24_e32 v122, 0x320, v120
	v_lshl_add_u32 v122, v121, 5, v122
	v_mul_u32_u24_e32 v123, 0x1800, v120
	v_lshl_add_u32 v123, v121, 4, v123
	ds_read_b128 v[124:127], v122 offset:26880
	ds_read_b128 v[128:131], v122 offset:26896
	v_add_u32_e32 v134, 0x200, v192
	v_cmp_gt_u32_e32 vcc, 0x100, v192
	v_mul_hi_i32 v135, v134, s71
	v_ashrrev_i32_e32 v135, 2, v135
	v_mul_u32_u24_e32 v136, 24, v135
	v_sub_u32_e32 v136, v134, v136
	v_mul_u32_u24_e32 v137, 0x320, v135
	v_lshl_add_u32 v137, v136, 5, v137
	v_mul_u32_u24_e32 v138, 0x1800, v135
	v_lshl_add_u32 v138, v136, 4, v138
	s_add_i32 s64, s64, 1
	s_waitcnt lgkmcnt(0)
	v_perm_b32 v140, v125, v124, v132
	v_perm_b32 v141, v127, v126, v132
	v_perm_b32 v142, v129, v128, v132
	v_perm_b32 v143, v131, v130, v132
	v_perm_b32 v144, v125, v124, v133
	v_perm_b32 v145, v127, v126, v133
	v_perm_b32 v146, v129, v128, v133
	v_perm_b32 v147, v131, v130, v133
	global_store_dwordx4 v123, v[140:143], s[2:3]
	global_store_dwordx4 v123, v[144:147], s[2:3] offset:3072
	s_cbranch_vccz .Lys_done
	ds_read_b128 v[124:127], v137 offset:26880
	ds_read_b128 v[128:131], v137 offset:26896
	s_waitcnt lgkmcnt(0)
	v_perm_b32 v140, v125, v124, v132
	v_perm_b32 v141, v127, v126, v132
	v_perm_b32 v142, v129, v128, v132
	v_perm_b32 v143, v131, v130, v132
	v_perm_b32 v144, v125, v124, v133
	v_perm_b32 v145, v127, v126, v133
	v_perm_b32 v146, v129, v128, v133
	v_perm_b32 v147, v131, v130, v133
	global_store_dwordx4 v138, v[140:143], s[2:3]
	global_store_dwordx4 v138, v[144:147], s[2:3] offset:3072
.Lys_done:
	s_cmp_eq_u32 s64, 32
	s_cbranch_scc1 .LBB0_816

; #define LAS __attribute__((address_space(3)))
; DI unsigned pk2(float a, float b) { f32x2 v = {a, b}; bf2_t r = __builtin_convertvector(v, bf2_t); return __builtin_bit_cast(unsigned, r); }
; DI void phase_rglru(const Params& p, unsigned char* shm) {
;     ...
;             if (tid < 192) {
; #pragma unroll 8
;                 for (int r = 0; r < 64; ++r) {
;                     const float om = __uint_as_float((unsigned)*(const LAS bf16_t*)(lds + LAo + r * TR + tid * 2) << 16);
;                     const float bt = __uint_as_float((unsigned)*(const LAS bf16_t*)(lds + BTo + r * TR + tid * 2) << 16);
;                     const float g = __uint_as_float((unsigned)*(const LAS bf16_t*)(lds + GT + r * TR + tid * 2) << 16);
;                     hst = (hst - om * hst) + bt;
;                     *(LAS bf16_t*)(lds + GT + r * TR + tid * 2) = (bf16_t)(pk2(hst * g, 0.f) & 0xffffu);
;                 }
.LBB0_851:
	s_andn2_saveexec_b64 s[2:3], s[2:3]
	s_cbranch_execz .LBB0_842
	v_mov_b32_e32 v126, 0
	v_mov_b32_e32 v127, 0
	v_mov_b32_e32 v128, 0
	v_mov_b32_e32 v129, 0
	v_mov_b32_e32 v130, 0
	v_mov_b32_e32 v131, 0
	v_mov_b32_e32 v132, 0
	v_mov_b32_e32 v133, 0
	v_mov_b32_e32 v134, 0
	v_mov_b32_e32 v135, 0
	v_mov_b32_e32 v136, 0
	v_mov_b32_e32 v137, 0
	v_mov_b32_e32 v138, 0
	v_mov_b32_e32 v139, 0
	v_mov_b32_e32 v140, 0
	v_mov_b32_e32 v141, 0
	v_mov_b32_e32 v142, 0
	v_mov_b32_e32 v143, 0
	v_mov_b32_e32 v144, 0
	v_mov_b32_e32 v145, 0
	v_mov_b32_e32 v146, 0
	v_mov_b32_e32 v147, 0
	v_mov_b32_e32 v148, 0
	v_mov_b32_e32 v149, 0
	v_add_u32_e32 v121, 0x13100, v176
	v_add_u32_e32 v122, 0x19500, v176
	v_add_u32_e32 v123, 0xcd00, v176
	v_lshlrev_b32_e32 v124, 1, v176
	v_add_u32_e32 v124, 0x6900, v124
	ds_read_u16_d16_hi v126, v121
	ds_read_u16_d16_hi v134, v122
	ds_read_u16_d16_hi v142, v123
	ds_read_u16_d16_hi v127, v121 offset:400
	ds_read_u16_d16_hi v135, v122 offset:400
	ds_read_u16_d16_hi v143, v123 offset:400
	ds_read_u16_d16_hi v128, v121 offset:800
	ds_read_u16_d16_hi v136, v122 offset:800
	ds_read_u16_d16_hi v144, v123 offset:800
	ds_read_u16_d16_hi v129, v121 offset:1200
	ds_read_u16_d16_hi v137, v122 offset:1200
	ds_read_u16_d16_hi v145, v123 offset:1200
	ds_read_u16_d16_hi v130, v121 offset:1600
	ds_read_u16_d16_hi v138, v122 offset:1600
	ds_read_u16_d16_hi v146, v123 offset:1600
	s_waitcnt lgkmcnt(12)
	v_fma_f32 v150, -v152, v126, v152
	v_add_f32_e32 v152, v150, v134
	v_mul_f32_e32 v170, v152, v142
	ds_read_u16_d16_hi v131, v121 offset:2000
	ds_read_u16_d16_hi v139, v122 offset:2000
	ds_read_u16_d16_hi v147, v123 offset:2000
	s_waitcnt lgkmcnt(12)
	v_fma_f32 v150, -v152, v127, v152
	v_add_f32_e32 v152, v150, v135
	v_mul_f32_e32 v171, v152, v143
	ds_read_u16_d16_hi v132, v121 offset:2400
	ds_read_u16_d16_hi v140, v122 offset:2400
	ds_read_u16_d16_hi v148, v123 offset:2400
	v_cvt_pk_bf16_f32 v151, v170, v171
	ds_write_b32 v124, v151
	s_waitcnt lgkmcnt(13)
	v_fma_f32 v150, -v152, v128, v152
	v_add_f32_e32 v152, v150, v136
	v_mul_f32_e32 v170, v152, v144
	ds_read_u16_d16_hi v133, v121 offset:2800
	ds_read_u16_d16_hi v141, v122 offset:2800
	ds_read_u16_d16_hi v149, v123 offset:2800
	s_waitcnt lgkmcnt(13)
	v_fma_f32 v150, -v152, v129, v152
	v_add_f32_e32 v152, v150, v137
	v_mul_f32_e32 v171, v152, v145
	ds_read_u16_d16_hi v126, v121 offset:3200
	ds_read_u16_d16_hi v134, v122 offset:3200
	ds_read_u16_d16_hi v142, v123 offset:3200
	v_cvt_pk_bf16_f32 v151, v170, v171
	ds_write_b32 v124, v151 offset:800
	s_waitcnt lgkmcnt(14)
	v_fma_f32 v150, -v152, v130, v152
	v_add_f32_e32 v152, v150, v138
	v_mul_f32_e32 v170, v152, v146
	ds_read_u16_d16_hi v127, v121 offset:3600
	ds_read_u16_d16_hi v135, v122 offset:3600
	ds_read_u16_d16_hi v143, v123 offset:3600
	s_waitcnt lgkmcnt(14)
	v_fma_f32 v150, -v152, v131, v152
	v_add_f32_e32 v152, v150, v139
	v_mul_f32_e32 v171, v152, v147
	ds_read_u16_d16_hi v128, v121 offset:4000
	ds_read_u16_d16_hi v136, v122 offset:4000
	ds_read_u16_d16_hi v144, v123 offset:4000
	v_cvt_pk_bf16_f32 v151, v170, v171
	ds_write_b32 v124, v151 offset:1600
	s_waitcnt lgkmcnt(15)
	v_fma_f32 v150, -v152, v132, v152
	v_add_f32_e32 v152, v150, v140
	v_mul_f32_e32 v170, v152, v148
	ds_read_u16_d16_hi v129, v121 offset:4400
	ds_read_u16_d16_hi v137, v122 offset:4400
	ds_read_u16_d16_hi v145, v123 offset:4400
	s_waitcnt lgkmcnt(14)
	v_fma_f32 v150, -v152, v133, v152
	v_add_f32_e32 v152, v150, v141
	v_mul_f32_e32 v171, v152, v149
	ds_read_u16_d16_hi v130, v121 offset:4800
	ds_read_u16_d16_hi v138, v122 offset:4800
	ds_read_u16_d16_hi v146, v123 offset:4800
	v_cvt_pk_bf16_f32 v151, v170, v171
	ds_write_b32 v124, v151 offset:2400
	s_waitcnt lgkmcnt(15)
	v_fma_f32 v150, -v152, v126, v152
	v_add_f32_e32 v152, v150, v134
	v_mul_f32_e32 v170, v152, v142
	ds_read_u16_d16_hi v131, v121 offset:5200
	ds_read_u16_d16_hi v139, v122 offset:5200
	ds_read_u16_d16_hi v147, v123 offset:5200
	s_waitcnt lgkmcnt(14)
	v_fma_f32 v150, -v152, v127, v152
	v_add_f32_e32 v152, v150, v135
	v_mul_f32_e32 v171, v152, v143
	ds_read_u16_d16_hi v132, v121 offset:5600
	ds_read_u16_d16_hi v140, v122 offset:5600
	ds_read_u16_d16_hi v148, v123 offset:5600
	v_cvt_pk_bf16_f32 v151, v170, v171
	ds_write_b32 v124, v151 offset:3200
	s_waitcnt lgkmcnt(15)
	v_fma_f32 v150, -v152, v128, v152
	v_add_f32_e32 v152, v150, v136
	v_mul_f32_e32 v170, v152, v144
	ds_read_u16_d16_hi v133, v121 offset:6000
	ds_read_u16_d16_hi v141, v122 offset:6000
	ds_read_u16_d16_hi v149, v123 offset:6000
	s_waitcnt lgkmcnt(14)
	v_fma_f32 v150, -v152, v129, v152
	v_add_f32_e32 v152, v150, v137
	v_mul_f32_e32 v171, v152, v145
	ds_read_u16_d16_hi v126, v121 offset:6400
	ds_read_u16_d16_hi v134, v122 offset:6400
	ds_read_u16_d16_hi v142, v123 offset:6400
	v_cvt_pk_bf16_f32 v151, v170, v171
	ds_write_b32 v124, v151 offset:4000
	s_waitcnt lgkmcnt(15)
	v_fma_f32 v150, -v152, v130, v152
	v_add_f32_e32 v152, v150, v138
	v_mul_f32_e32 v170, v152, v146
	ds_read_u16_d16_hi v127, v121 offset:6800
	ds_read_u16_d16_hi v135, v122 offset:6800
	ds_read_u16_d16_hi v143, v123 offset:6800
	s_waitcnt lgkmcnt(14)
	v_fma_f32 v150, -v152, v131, v152
	v_add_f32_e32 v152, v150, v139
	v_mul_f32_e32 v171, v152, v147
	ds_read_u16_d16_hi v128, v121 offset:7200
	ds_read_u16_d16_hi v136, v122 offset:7200
	ds_read_u16_d16_hi v144, v123 offset:7200
	v_cvt_pk_bf16_f32 v151, v170, v171
	ds_write_b32 v124, v151 offset:4800
	s_waitcnt lgkmcnt(15)
	v_fma_f32 v150, -v152, v132, v152
	v_add_f32_e32 v152, v150, v140
	v_mul_f32_e32 v170, v152, v148
	ds_read_u16_d16_hi v129, v121 offset:7600
	ds_read_u16_d16_hi v137, v122 offset:7600
	ds_read_u16_d16_hi v145, v123 offset:7600
	s_waitcnt lgkmcnt(14)
; #define LAS __attribute__((address_space(3)))
; DI unsigned pk2(float a, float b) { f32x2 v = {a, b}; bf2_t r = __builtin_convertvector(v, bf2_t); return __builtin_bit_cast(unsigned, r); }
; DI void phase_rglru(const Params& p, unsigned char* shm) {
;     ...
;             if (tid < 192) {
; #pragma unroll 8
;                 for (int r = 0; r < 64; ++r) {
;                     const float om = __uint_as_float((unsigned)*(const LAS bf16_t*)(lds + LAo + r * TR + tid * 2) << 16);
;                     const float bt = __uint_as_float((unsigned)*(const LAS bf16_t*)(lds + BTo + r * TR + tid * 2) << 16);
;                     const float g = __uint_as_float((unsigned)*(const LAS bf16_t*)(lds + GT + r * TR + tid * 2) << 16);
;                     hst = (hst - om * hst) + bt;
;                     *(LAS bf16_t*)(lds + GT + r * TR + tid * 2) = (bf16_t)(pk2(hst * g, 0.f) & 0xffffu);
;                 }
	v_fma_f32 v150, -v152, v133, v152
	v_add_f32_e32 v152, v150, v141
	v_mul_f32_e32 v171, v152, v149
	ds_read_u16_d16_hi v130, v121 offset:8000
	ds_read_u16_d16_hi v138, v122 offset:8000
	ds_read_u16_d16_hi v146, v123 offset:8000
	v_cvt_pk_bf16_f32 v151, v170, v171
	ds_write_b32 v124, v151 offset:5600
	s_waitcnt lgkmcnt(15)
	v_fma_f32 v150, -v152, v126, v152
	v_add_f32_e32 v152, v150, v134
	v_mul_f32_e32 v170, v152, v142
	ds_read_u16_d16_hi v131, v121 offset:8400
	ds_read_u16_d16_hi v139, v122 offset:8400
	ds_read_u16_d16_hi v147, v123 offset:8400
	s_waitcnt lgkmcnt(14)
	v_fma_f32 v150, -v152, v127, v152
	v_add_f32_e32 v152, v150, v135
	v_mul_f32_e32 v171, v152, v143
	ds_read_u16_d16_hi v132, v121 offset:8800
	ds_read_u16_d16_hi v140, v122 offset:8800
	ds_read_u16_d16_hi v148, v123 offset:8800
	v_cvt_pk_bf16_f32 v151, v170, v171
	ds_write_b32 v124, v151 offset:6400
	s_waitcnt lgkmcnt(15)
	v_fma_f32 v150, -v152, v128, v152
	v_add_f32_e32 v152, v150, v136
	v_mul_f32_e32 v170, v152, v144
	ds_read_u16_d16_hi v133, v121 offset:9200
	ds_read_u16_d16_hi v141, v122 offset:9200
	ds_read_u16_d16_hi v149, v123 offset:9200
	s_waitcnt lgkmcnt(14)
	v_fma_f32 v150, -v152, v129, v152
	v_add_f32_e32 v152, v150, v137
	v_mul_f32_e32 v171, v152, v145
	ds_read_u16_d16_hi v126, v121 offset:9600
	ds_read_u16_d16_hi v134, v122 offset:9600
	ds_read_u16_d16_hi v142, v123 offset:9600
	v_cvt_pk_bf16_f32 v151, v170, v171
	ds_write_b32 v124, v151 offset:7200
	s_waitcnt lgkmcnt(15)
	v_fma_f32 v150, -v152, v130, v152
	v_add_f32_e32 v152, v150, v138
	v_mul_f32_e32 v170, v152, v146
	ds_read_u16_d16_hi v127, v121 offset:10000
	ds_read_u16_d16_hi v135, v122 offset:10000
	ds_read_u16_d16_hi v143, v123 offset:10000
	s_waitcnt lgkmcnt(14)
	v_fma_f32 v150, -v152, v131, v152
	v_add_f32_e32 v152, v150, v139
	v_mul_f32_e32 v171, v152, v147
	ds_read_u16_d16_hi v128, v121 offset:10400
	ds_read_u16_d16_hi v136, v122 offset:10400
	ds_read_u16_d16_hi v144, v123 offset:10400
	v_cvt_pk_bf16_f32 v151, v170, v171
	ds_write_b32 v124, v151 offset:8000
	s_waitcnt lgkmcnt(15)
	v_fma_f32 v150, -v152, v132, v152
	v_add_f32_e32 v152, v150, v140
	v_mul_f32_e32 v170, v152, v148
	ds_read_u16_d16_hi v129, v121 offset:10800
	ds_read_u16_d16_hi v137, v122 offset:10800
	ds_read_u16_d16_hi v145, v123 offset:10800
	s_waitcnt lgkmcnt(14)
	v_fma_f32 v150, -v152, v133, v152
	v_add_f32_e32 v152, v150, v141
	v_mul_f32_e32 v171, v152, v149
	ds_read_u16_d16_hi v130, v121 offset:11200
	ds_read_u16_d16_hi v138, v122 offset:11200
	ds_read_u16_d16_hi v146, v123 offset:11200
	v_cvt_pk_bf16_f32 v151, v170, v171
	ds_write_b32 v124, v151 offset:8800
	s_waitcnt lgkmcnt(15)
	v_fma_f32 v150, -v152, v126, v152
	v_add_f32_e32 v152, v150, v134
	v_mul_f32_e32 v170, v152, v142
	ds_read_u16_d16_hi v131, v121 offset:11600
	ds_read_u16_d16_hi v139, v122 offset:11600
	ds_read_u16_d16_hi v147, v123 offset:11600
	s_waitcnt lgkmcnt(14)
	v_fma_f32 v150, -v152, v127, v152
	v_add_f32_e32 v152, v150, v135
	v_mul_f32_e32 v171, v152, v143
	ds_read_u16_d16_hi v132, v121 offset:12000
	ds_read_u16_d16_hi v140, v122 offset:12000
	ds_read_u16_d16_hi v148, v123 offset:12000
	v_cvt_pk_bf16_f32 v151, v170, v171
	ds_write_b32 v124, v151 offset:9600
	s_waitcnt lgkmcnt(15)
	v_fma_f32 v150, -v152, v128, v152
	v_add_f32_e32 v152, v150, v136
	v_mul_f32_e32 v170, v152, v144
	ds_read_u16_d16_hi v133, v121 offset:12400
	ds_read_u16_d16_hi v141, v122 offset:12400
	ds_read_u16_d16_hi v149, v123 offset:12400
	s_waitcnt lgkmcnt(14)
	v_fma_f32 v150, -v152, v129, v152
	v_add_f32_e32 v152, v150, v137
	v_mul_f32_e32 v171, v152, v145
	ds_read_u16_d16_hi v126, v121 offset:12800
	ds_read_u16_d16_hi v134, v122 offset:12800
	ds_read_u16_d16_hi v142, v123 offset:12800
	v_cvt_pk_bf16_f32 v151, v170, v171
	ds_write_b32 v124, v151 offset:10400
	s_waitcnt lgkmcnt(15)
	v_fma_f32 v150, -v152, v130, v152
	v_add_f32_e32 v152, v150, v138
	v_mul_f32_e32 v170, v152, v146
	ds_read_u16_d16_hi v127, v121 offset:13200
	ds_read_u16_d16_hi v135, v122 offset:13200
	ds_read_u16_d16_hi v143, v123 offset:13200
	s_waitcnt lgkmcnt(14)
	v_fma_f32 v150, -v152, v131, v152
	v_add_f32_e32 v152, v150, v139
	v_mul_f32_e32 v171, v152, v147
	ds_read_u16_d16_hi v128, v121 offset:13600
	ds_read_u16_d16_hi v136, v122 offset:13600
	ds_read_u16_d16_hi v144, v123 offset:13600
	v_cvt_pk_bf16_f32 v151, v170, v171
	ds_write_b32 v124, v151 offset:11200
	s_waitcnt lgkmcnt(15)
	v_fma_f32 v150, -v152, v132, v152
	v_add_f32_e32 v152, v150, v140
	v_mul_f32_e32 v170, v152, v148
	ds_read_u16_d16_hi v129, v121 offset:14000
	ds_read_u16_d16_hi v137, v122 offset:14000
	ds_read_u16_d16_hi v145, v123 offset:14000
	s_waitcnt lgkmcnt(14)
	v_fma_f32 v150, -v152, v133, v152
	v_add_f32_e32 v152, v150, v141
	v_mul_f32_e32 v171, v152, v149
	ds_read_u16_d16_hi v130, v121 offset:14400
	ds_read_u16_d16_hi v138, v122 offset:14400
	ds_read_u16_d16_hi v146, v123 offset:14400
	v_cvt_pk_bf16_f32 v151, v170, v171
	ds_write_b32 v124, v151 offset:12000
	s_waitcnt lgkmcnt(15)
	v_fma_f32 v150, -v152, v126, v152
	v_add_f32_e32 v152, v150, v134
	v_mul_f32_e32 v170, v152, v142
	ds_read_u16_d16_hi v131, v121 offset:14800
	ds_read_u16_d16_hi v139, v122 offset:14800
	ds_read_u16_d16_hi v147, v123 offset:14800
	s_waitcnt lgkmcnt(14)
	v_fma_f32 v150, -v152, v127, v152
	v_add_f32_e32 v152, v150, v135
	v_mul_f32_e32 v171, v152, v143
	ds_read_u16_d16_hi v132, v121 offset:15200
	ds_read_u16_d16_hi v140, v122 offset:15200
	ds_read_u16_d16_hi v148, v123 offset:15200
	v_cvt_pk_bf16_f32 v151, v170, v171
	ds_write_b32 v124, v151 offset:12800
	s_waitcnt lgkmcnt(15)
; #define LAS __attribute__((address_space(3)))
; DI unsigned pk2(float a, float b) { f32x2 v = {a, b}; bf2_t r = __builtin_convertvector(v, bf2_t); return __builtin_bit_cast(unsigned, r); }
; DI void phase_rglru(const Params& p, unsigned char* shm) {
;     ...
;             if (tid < 192) {
; #pragma unroll 8
;                 for (int r = 0; r < 64; ++r) {
;                     const float om = __uint_as_float((unsigned)*(const LAS bf16_t*)(lds + LAo + r * TR + tid * 2) << 16);
;                     const float bt = __uint_as_float((unsigned)*(const LAS bf16_t*)(lds + BTo + r * TR + tid * 2) << 16);
;                     const float g = __uint_as_float((unsigned)*(const LAS bf16_t*)(lds + GT + r * TR + tid * 2) << 16);
;                     hst = (hst - om * hst) + bt;
;                     *(LAS bf16_t*)(lds + GT + r * TR + tid * 2) = (bf16_t)(pk2(hst * g, 0.f) & 0xffffu);
;                 }
	v_fma_f32 v150, -v152, v128, v152
	v_add_f32_e32 v152, v150, v136
	v_mul_f32_e32 v170, v152, v144
	ds_read_u16_d16_hi v133, v121 offset:15600
	ds_read_u16_d16_hi v141, v122 offset:15600
	ds_read_u16_d16_hi v149, v123 offset:15600
	s_waitcnt lgkmcnt(14)
	v_fma_f32 v150, -v152, v129, v152
	v_add_f32_e32 v152, v150, v137
	v_mul_f32_e32 v171, v152, v145
	ds_read_u16_d16_hi v126, v121 offset:16000
	ds_read_u16_d16_hi v134, v122 offset:16000
	ds_read_u16_d16_hi v142, v123 offset:16000
	v_cvt_pk_bf16_f32 v151, v170, v171
	ds_write_b32 v124, v151 offset:13600
	s_waitcnt lgkmcnt(15)
	v_fma_f32 v150, -v152, v130, v152
	v_add_f32_e32 v152, v150, v138
	v_mul_f32_e32 v170, v152, v146
	ds_read_u16_d16_hi v127, v121 offset:16400
	ds_read_u16_d16_hi v135, v122 offset:16400
	ds_read_u16_d16_hi v143, v123 offset:16400
	s_waitcnt lgkmcnt(14)
	v_fma_f32 v150, -v152, v131, v152
	v_add_f32_e32 v152, v150, v139
	v_mul_f32_e32 v171, v152, v147
	ds_read_u16_d16_hi v128, v121 offset:16800
	ds_read_u16_d16_hi v136, v122 offset:16800
	ds_read_u16_d16_hi v144, v123 offset:16800
	v_cvt_pk_bf16_f32 v151, v170, v171
	ds_write_b32 v124, v151 offset:14400
	s_waitcnt lgkmcnt(15)
	v_fma_f32 v150, -v152, v132, v152
	v_add_f32_e32 v152, v150, v140
	v_mul_f32_e32 v170, v152, v148
	ds_read_u16_d16_hi v129, v121 offset:17200
	ds_read_u16_d16_hi v137, v122 offset:17200
	ds_read_u16_d16_hi v145, v123 offset:17200
	s_waitcnt lgkmcnt(14)
	v_fma_f32 v150, -v152, v133, v152
	v_add_f32_e32 v152, v150, v141
	v_mul_f32_e32 v171, v152, v149
	ds_read_u16_d16_hi v130, v121 offset:17600
	ds_read_u16_d16_hi v138, v122 offset:17600
	ds_read_u16_d16_hi v146, v123 offset:17600
	v_cvt_pk_bf16_f32 v151, v170, v171
	ds_write_b32 v124, v151 offset:15200
	s_waitcnt lgkmcnt(15)
	v_fma_f32 v150, -v152, v126, v152
	v_add_f32_e32 v152, v150, v134
	v_mul_f32_e32 v170, v152, v142
	ds_read_u16_d16_hi v131, v121 offset:18000
	ds_read_u16_d16_hi v139, v122 offset:18000
	ds_read_u16_d16_hi v147, v123 offset:18000
	s_waitcnt lgkmcnt(14)
	v_fma_f32 v150, -v152, v127, v152
	v_add_f32_e32 v152, v150, v135
	v_mul_f32_e32 v171, v152, v143
	ds_read_u16_d16_hi v132, v121 offset:18400
	ds_read_u16_d16_hi v140, v122 offset:18400
	ds_read_u16_d16_hi v148, v123 offset:18400
	v_cvt_pk_bf16_f32 v151, v170, v171
	ds_write_b32 v124, v151 offset:16000
	s_waitcnt lgkmcnt(15)
	v_fma_f32 v150, -v152, v128, v152
	v_add_f32_e32 v152, v150, v136
	v_mul_f32_e32 v170, v152, v144
	ds_read_u16_d16_hi v133, v121 offset:18800
	ds_read_u16_d16_hi v141, v122 offset:18800
	ds_read_u16_d16_hi v149, v123 offset:18800
	s_waitcnt lgkmcnt(14)
	v_fma_f32 v150, -v152, v129, v152
	v_add_f32_e32 v152, v150, v137
	v_mul_f32_e32 v171, v152, v145
	ds_read_u16_d16_hi v126, v121 offset:19200
	ds_read_u16_d16_hi v134, v122 offset:19200
	ds_read_u16_d16_hi v142, v123 offset:19200
	v_cvt_pk_bf16_f32 v151, v170, v171
	ds_write_b32 v124, v151 offset:16800
	s_waitcnt lgkmcnt(15)
	v_fma_f32 v150, -v152, v130, v152
	v_add_f32_e32 v152, v150, v138
	v_mul_f32_e32 v170, v152, v146
	ds_read_u16_d16_hi v127, v121 offset:19600
	ds_read_u16_d16_hi v135, v122 offset:19600
	ds_read_u16_d16_hi v143, v123 offset:19600
	s_waitcnt lgkmcnt(14)
	v_fma_f32 v150, -v152, v131, v152
	v_add_f32_e32 v152, v150, v139
	v_mul_f32_e32 v171, v152, v147
	ds_read_u16_d16_hi v128, v121 offset:20000
	ds_read_u16_d16_hi v136, v122 offset:20000
	ds_read_u16_d16_hi v144, v123 offset:20000
	v_cvt_pk_bf16_f32 v151, v170, v171
	ds_write_b32 v124, v151 offset:17600
	s_waitcnt lgkmcnt(15)
	v_fma_f32 v150, -v152, v132, v152
	v_add_f32_e32 v152, v150, v140
	v_mul_f32_e32 v170, v152, v148
	ds_read_u16_d16_hi v129, v121 offset:20400
	ds_read_u16_d16_hi v137, v122 offset:20400
	ds_read_u16_d16_hi v145, v123 offset:20400
	s_waitcnt lgkmcnt(14)
	v_fma_f32 v150, -v152, v133, v152
	v_add_f32_e32 v152, v150, v141
	v_mul_f32_e32 v171, v152, v149
	ds_read_u16_d16_hi v130, v121 offset:20800
	ds_read_u16_d16_hi v138, v122 offset:20800
	ds_read_u16_d16_hi v146, v123 offset:20800
	v_cvt_pk_bf16_f32 v151, v170, v171
	ds_write_b32 v124, v151 offset:18400
	s_waitcnt lgkmcnt(15)
; #define LAS __attribute__((address_space(3)))
; DI unsigned pk2(float a, float b) { f32x2 v = {a, b}; bf2_t r = __builtin_convertvector(v, bf2_t); return __builtin_bit_cast(unsigned, r); }
; DI void phase_rglru(const Params& p, unsigned char* shm) {
;     ...
;             if (tid < 192) {
; #pragma unroll 8
;                 for (int r = 0; r < 64; ++r) {
;                     const float om = __uint_as_float((unsigned)*(const LAS bf16_t*)(lds + LAo + r * TR + tid * 2) << 16);
;                     const float bt = __uint_as_float((unsigned)*(const LAS bf16_t*)(lds + BTo + r * TR + tid * 2) << 16);
;                     const float g = __uint_as_float((unsigned)*(const LAS bf16_t*)(lds + GT + r * TR + tid * 2) << 16);
;                     hst = (hst - om * hst) + bt;
;                     *(LAS bf16_t*)(lds + GT + r * TR + tid * 2) = (bf16_t)(pk2(hst * g, 0.f) & 0xffffu);
;                 }
	v_fma_f32 v150, -v152, v126, v152
	v_add_f32_e32 v152, v150, v134
	v_mul_f32_e32 v170, v152, v142
	ds_read_u16_d16_hi v131, v121 offset:21200
	ds_read_u16_d16_hi v139, v122 offset:21200
	ds_read_u16_d16_hi v147, v123 offset:21200
	s_waitcnt lgkmcnt(14)
	v_fma_f32 v150, -v152, v127, v152
	v_add_f32_e32 v152, v150, v135
	v_mul_f32_e32 v171, v152, v143
	ds_read_u16_d16_hi v132, v121 offset:21600
	ds_read_u16_d16_hi v140, v122 offset:21600
	ds_read_u16_d16_hi v148, v123 offset:21600
	v_cvt_pk_bf16_f32 v151, v170, v171
	ds_write_b32 v124, v151 offset:19200
	s_waitcnt lgkmcnt(15)
	v_fma_f32 v150, -v152, v128, v152
	v_add_f32_e32 v152, v150, v136
	v_mul_f32_e32 v170, v152, v144
	ds_read_u16_d16_hi v133, v121 offset:22000
	ds_read_u16_d16_hi v141, v122 offset:22000
	ds_read_u16_d16_hi v149, v123 offset:22000
	s_waitcnt lgkmcnt(14)
	v_fma_f32 v150, -v152, v129, v152
	v_add_f32_e32 v152, v150, v137
	v_mul_f32_e32 v171, v152, v145
	ds_read_u16_d16_hi v126, v121 offset:22400
	ds_read_u16_d16_hi v134, v122 offset:22400
	ds_read_u16_d16_hi v142, v123 offset:22400
	v_cvt_pk_bf16_f32 v151, v170, v171
	ds_write_b32 v124, v151 offset:20000
	s_waitcnt lgkmcnt(15)
	v_fma_f32 v150, -v152, v130, v152
	v_add_f32_e32 v152, v150, v138
	v_mul_f32_e32 v170, v152, v146
	ds_read_u16_d16_hi v127, v121 offset:22800
	ds_read_u16_d16_hi v135, v122 offset:22800
	ds_read_u16_d16_hi v143, v123 offset:22800
	s_waitcnt lgkmcnt(14)
	v_fma_f32 v150, -v152, v131, v152
	v_add_f32_e32 v152, v150, v139
	v_mul_f32_e32 v171, v152, v147
	ds_read_u16_d16_hi v128, v121 offset:23200
	ds_read_u16_d16_hi v136, v122 offset:23200
	ds_read_u16_d16_hi v144, v123 offset:23200
	v_cvt_pk_bf16_f32 v151, v170, v171
	ds_write_b32 v124, v151 offset:20800
	s_waitcnt lgkmcnt(15)
	v_fma_f32 v150, -v152, v132, v152
	v_add_f32_e32 v152, v150, v140
	v_mul_f32_e32 v170, v152, v148
	ds_read_u16_d16_hi v129, v121 offset:23600
	ds_read_u16_d16_hi v137, v122 offset:23600
	ds_read_u16_d16_hi v145, v123 offset:23600
	s_waitcnt lgkmcnt(14)
	v_fma_f32 v150, -v152, v133, v152
	v_add_f32_e32 v152, v150, v141
	v_mul_f32_e32 v171, v152, v149
	ds_read_u16_d16_hi v130, v121 offset:24000
	ds_read_u16_d16_hi v138, v122 offset:24000
	ds_read_u16_d16_hi v146, v123 offset:24000
	v_cvt_pk_bf16_f32 v151, v170, v171
	ds_write_b32 v124, v151 offset:21600
	s_waitcnt lgkmcnt(15)
	v_fma_f32 v150, -v152, v126, v152
	v_add_f32_e32 v152, v150, v134
	v_mul_f32_e32 v170, v152, v142
	ds_read_u16_d16_hi v131, v121 offset:24400
	ds_read_u16_d16_hi v139, v122 offset:24400
	ds_read_u16_d16_hi v147, v123 offset:24400
	s_waitcnt lgkmcnt(14)
	v_fma_f32 v150, -v152, v127, v152
	v_add_f32_e32 v152, v150, v135
	v_mul_f32_e32 v171, v152, v143
	ds_read_u16_d16_hi v132, v121 offset:24800
	ds_read_u16_d16_hi v140, v122 offset:24800
	ds_read_u16_d16_hi v148, v123 offset:24800
	v_cvt_pk_bf16_f32 v151, v170, v171
	ds_write_b32 v124, v151 offset:22400
	s_waitcnt lgkmcnt(15)
	v_fma_f32 v150, -v152, v128, v152
	v_add_f32_e32 v152, v150, v136
	v_mul_f32_e32 v170, v152, v144
	ds_read_u16_d16_hi v133, v121 offset:25200
	ds_read_u16_d16_hi v141, v122 offset:25200
	ds_read_u16_d16_hi v149, v123 offset:25200
	s_waitcnt lgkmcnt(14)
	v_fma_f32 v150, -v152, v129, v152
	v_add_f32_e32 v152, v150, v137
	v_mul_f32_e32 v171, v152, v145
	v_cvt_pk_bf16_f32 v151, v170, v171
	ds_write_b32 v124, v151 offset:23200
	s_waitcnt lgkmcnt(12)
	v_fma_f32 v150, -v152, v130, v152
	v_add_f32_e32 v152, v150, v138
	v_mul_f32_e32 v170, v152, v146
	s_waitcnt lgkmcnt(8)
	v_fma_f32 v150, -v152, v131, v152
	v_add_f32_e32 v152, v150, v139
	v_mul_f32_e32 v171, v152, v147
	v_cvt_pk_bf16_f32 v151, v170, v171
	ds_write_b32 v124, v151 offset:24000
	s_waitcnt lgkmcnt(6)
	v_fma_f32 v150, -v152, v132, v152
	v_add_f32_e32 v152, v150, v140
	v_mul_f32_e32 v170, v152, v148
	s_waitcnt lgkmcnt(2)
	v_fma_f32 v150, -v152, v133, v152
	v_add_f32_e32 v152, v150, v141
	v_mul_f32_e32 v171, v152, v149
	v_cvt_pk_bf16_f32 v151, v170, v171
	ds_write_b32 v124, v151 offset:24800
	s_branch .LBB0_842
